# v57 + P3 decode attention: KV-cache copy rounds 2-4 issue their loads together (renamed registers, counted waits) instead of one (K,V) pair per memory round trip
# speedup vs baseline: 1.0040x; 1.0040x over previous
; #define LAS __attribute__((address_space(3)))
; DI float bf2f(unsigned short u) { return __uint_as_float(((unsigned)u) << 16); }
; DI void attn_decode_unit(LAS unsigned char* lds, const bf16_t* Z, const float* ck, const float* cv, bf16_t* MIX, const float* gq, const float* gk, const float* sinks, float* o_k, float* o_v, int b, int kh, int tid) {
;     ...
; #pragma unroll
;     for (int k = 0; k < 4; ++k) {
;         const int it = k * 512 + tid, w = it >> 4, c4 = (it & 15) * 4;
;         const size_t src = ((size_t)(b * 128 + w) * 2 + kh) * 64 + c4;
;         const f32x4 k4 = *(const f32x4*)(ck + src), v4 = *(const f32x4*)(cv + src);
;         *(LAS f32x4*)(Kc + w * 68 + c4) = k4; *(LAS f32x4*)(Vc + w * 64 + c4) = v4;
;         if (w >= 1) { const size_t dst = ((size_t)(b * 128 + w - 1) * 2 + kh) * 64 + c4; *(f32x4*)(o_k + dst) = k4; *(f32x4*)(o_v + dst) = v4; }
;     }
;     const bf16_t* zrow = Z + (size_t)(LP + b) * INW;
;     const size_t dnew = ((size_t)(b * 128 + 127) * 2 + kh) * 64 + lane;
;     if (wid == 0) { const float kx = bf2f(zrow[C_AK + kh * 64 + lane]); const float ss = wave_sum(kx * kx); const float kn = kx * rsqrtf(ss * (1.0f / 64.0f) + EPS) * gk[lane];
;         Kc[128 * 68 + lane] = kn; o_k[dnew] = kn; }
;     if (wid == 1) { const float vx = bf2f(zrow[C_AV + kh * 64 + lane]); Vc[128 * 64 + lane] = vx; o_v[dnew] = vx; }
.LBB0_314:
	s_or_b64 exec, exec, s[4:5]
	v_or_b32_e32 v0, s6, v42
	v_ashrrev_i32_e32 v1, 31, v0
	v_lshlrev_b64 v[0:1], 7, v[0:1]
	v_or_b32_e32 v0, v0, v40
	v_or_b32_e32 v2, s20, v0
	v_mov_b32_e32 v3, v1
	v_lshlrev_b64 v[6:7], 2, v[2:3]
	v_lshl_add_u64 v[2:3], s[48:49], 0, v[6:7]
	global_load_dwordx4 v[2:5], v[2:3], off
	v_lshl_add_u64 v[6:7], s[50:51], 0, v[6:7]
	global_load_dwordx4 v[10:13], v[6:7], off
	v_or_b32_e32 v6, s6, v43
	v_ashrrev_i32_e32 v7, 31, v6
	v_lshlrev_b64 v[6:7], 7, v[6:7]
	v_or_b32_e32 v6, v6, v40
	v_lshl_add_u64 v[0:1], v[0:1], 0, s[20:21]
	v_mov_b32_e32 v29, v7
	v_or_b32_e32 v28, s20, v6
	v_lshl_add_u64 v[0:1], v[0:1], 2, s[22:23]
	v_lshlrev_b64 v[28:29], 2, v[28:29]
	v_lshl_add_u64 v[30:31], s[14:15], 0, v[0:1]
	v_lshl_add_u64 v[0:1], s[16:17], 0, v[0:1]
	v_lshl_add_u64 v[32:33], s[48:49], 0, v[28:29]
	v_lshl_add_u64 v[34:35], s[50:51], 0, v[28:29]
	v_add_u32_e32 v36, s6, v44
	v_ashrrev_i32_e32 v37, 31, v36
	v_lshlrev_b64 v[68:69], 7, v[36:37]
	v_or_b32_e32 v68, v68, v40
	v_lshl_add_u64 v[6:7], v[6:7], 0, s[20:21]
	v_mov_b32_e32 v37, v69
	v_or_b32_e32 v36, s20, v68
	v_lshlrev_b64 v[36:37], 2, v[36:37]
	v_lshl_add_u64 v[64:65], s[48:49], 0, v[36:37]
	v_lshl_add_u64 v[66:67], s[50:51], 0, v[36:37]
	s_add_i32 s24, s7, 0x2000
	s_mul_i32 s4, s24, 0x2a00
	s_mul_hi_i32 s5, s24, 0x2a00
	s_add_u32 s4, s54, s4
	s_addc_u32 s5, s55, s5
	s_or_b32 s6, s6, 0x7f
	s_ashr_i32 s7, s6, 31
	v_mov_b32_e32 v72, s20
	s_lshl_b64 s[6:7], s[6:7], 7
	v_add_u32_e32 v8, v56, v57
	v_add_u32_e32 v25, v56, v58
	v_add_u32_e32 v63, v56, v59
	v_add_u32_e32 v70, v56, v60
	v_add_u32_e32 v71, v56, v61
	global_load_dwordx4 v[208:211], v[32:33], off
	s_nop 0
	global_load_dwordx4 v[212:215], v[34:35], off
	s_nop 0
	global_load_dwordx4 v[216:219], v[64:65], off
	s_nop 0
	global_load_dwordx4 v[220:223], v[66:67], off
	s_nop 0
	s_waitcnt vmcnt(5)
	global_store_dwordx4 v[30:31], v[2:5], off
	s_waitcnt vmcnt(5)
	global_store_dwordx4 v[0:1], v[10:13], off
	s_nop 0
	v_mov_b64_e32 v[0:1], s[22:23]
	v_lshl_add_u64 v[6:7], v[6:7], 2, v[0:1]
	v_lshl_add_u64 v[38:39], s[14:15], 0, v[6:7]
	v_lshl_add_u64 v[6:7], s[16:17], 0, v[6:7]
	s_waitcnt vmcnt(5)
	global_store_dwordx4 v[38:39], v[208:211], off
	s_waitcnt vmcnt(5)
	global_store_dwordx4 v[6:7], v[212:215], off
	s_nop 0
	v_lshl_add_u64 v[6:7], v[68:69], 0, s[20:21]
	v_lshl_add_u64 v[0:1], v[6:7], 2, v[0:1]
	v_lshl_add_u64 v[6:7], s[14:15], 0, v[0:1]
	v_lshl_add_u64 v[68:69], s[16:17], 0, v[0:1]
	v_or3_b32 v1, s7, 0, 0
	v_or3_b32 v0, s6, v72, v152
	ds_write_b128 v8, v[2:5]
	ds_write_b128 v25, v[10:13] offset:35088
	ds_write_b128 v54, v[208:211] offset:17408
	ds_write_b128 v63, v[212:215] offset:35088
	s_waitcnt vmcnt(5)
	ds_write_b128 v70, v[216:219]
	s_waitcnt vmcnt(4)
	ds_write_b128 v71, v[220:223] offset:35088
	global_store_dwordx4 v[6:7], v[216:219], off
	global_store_dwordx4 v[68:69], v[220:223], off
	s_and_saveexec_b64 s[6:7], s[0:1]
	s_cbranch_execz .LBB0_316
	v_or_b32_e32 v2, s20, v253
	v_lshlrev_b32_e32 v2, 1, v2
	global_load_ushort v2, v2, s[4:5] offset:2048
	s_nop 0
	global_load_dword v4, v[20:21], off
	s_waitcnt vmcnt(1)
	v_lshlrev_b32_e32 v5, 16, v2
	v_mul_f32_e32 v2, v5, v5
	ds_bpermute_b32 v2, v14, v2
	s_waitcnt lgkmcnt(0)
	v_fmac_f32_e32 v2, v5, v5
	ds_bpermute_b32 v3, v15, v2
	s_waitcnt lgkmcnt(0)
	v_add_f32_e32 v2, v2, v3
	ds_bpermute_b32 v3, v16, v2
	s_waitcnt lgkmcnt(0)
	v_add_f32_e32 v2, v2, v3
	ds_bpermute_b32 v3, v17, v2
	s_waitcnt lgkmcnt(0)
	v_add_f32_e32 v2, v2, v3
	ds_bpermute_b32 v3, v18, v2
	s_waitcnt lgkmcnt(0)
	v_add_f32_e32 v2, v2, v3
	ds_bpermute_b32 v3, v19, v2
	s_waitcnt lgkmcnt(0)
	v_add_f32_e32 v2, v2, v3
	v_fmamk_f32 v2, v2, 0x3c800000, v27
	v_mul_f32_e32 v3, 0x4b800000, v2
	v_cmp_gt_f32_e32 vcc, s12, v2
	s_nop 1
	v_cndmask_b32_e32 v2, v2, v3, vcc
	v_rsq_f32_e32 v6, v2
	v_lshl_add_u64 v[2:3], v[0:1], 2, s[14:15]
	v_mul_f32_e32 v7, 0x45800000, v6
	v_cndmask_b32_e32 v6, v6, v7, vcc
	v_mul_f32_e32 v5, v6, v5
	s_waitcnt vmcnt(0)
	v_mul_f32_e32 v4, v4, v5
	ds_write_b32 v45, v4 offset:34816
	global_store_dword v[2:3], v4, off

; #define LAS __attribute__((address_space(3)))
; DI float bf2f(unsigned short u) { return __uint_as_float(((unsigned)u) << 16); }
; DI void attn_decode_unit(LAS unsigned char* lds, const bf16_t* Z, const float* ck, const float* cv, bf16_t* MIX, const float* gq, const float* gk, const float* sinks, float* o_k, float* o_v, int b, int kh, int tid) {
;     ...
; #pragma unroll
;     for (int k = 0; k < 4; ++k) {
;         const int it = k * 512 + tid, w = it >> 4, c4 = (it & 15) * 4;
;         const size_t src = ((size_t)(b * 128 + w) * 2 + kh) * 64 + c4;
;         const f32x4 k4 = *(const f32x4*)(ck + src), v4 = *(const f32x4*)(cv + src);
;         *(LAS f32x4*)(Kc + w * 68 + c4) = k4; *(LAS f32x4*)(Vc + w * 64 + c4) = v4;
;         if (w >= 1) { const size_t dst = ((size_t)(b * 128 + w - 1) * 2 + kh) * 64 + c4; *(f32x4*)(o_k + dst) = k4; *(f32x4*)(o_v + dst) = v4; }
;     }
;     const bf16_t* zrow = Z + (size_t)(LP + b) * INW;
;     const size_t dnew = ((size_t)(b * 128 + 127) * 2 + kh) * 64 + lane;
;     if (wid == 0) { const float kx = bf2f(zrow[C_AK + kh * 64 + lane]); const float ss = wave_sum(kx * kx); const float kn = kx * rsqrtf(ss * (1.0f / 64.0f) + EPS) * gk[lane];
;         Kc[128 * 68 + lane] = kn; o_k[dnew] = kn; }
;     if (wid == 1) { const float vx = bf2f(zrow[C_AV + kh * 64 + lane]); Vc[128 * 64 + lane] = vx; o_v[dnew] = vx; }
.LBB0_338:
	s_or_b64 exec, exec, s[2:3]
	v_or_b32_e32 v0, s4, v42
	v_ashrrev_i32_e32 v1, 31, v0
	v_lshlrev_b64 v[0:1], 7, v[0:1]
	v_or_b32_e32 v0, v0, v40
	v_or_b32_e32 v2, s6, v0
	v_mov_b32_e32 v3, v1
	v_lshlrev_b64 v[6:7], 2, v[2:3]
	v_lshl_add_u64 v[2:3], s[48:49], 0, v[6:7]
	global_load_dwordx4 v[2:5], v[2:3], off
	v_lshl_add_u64 v[6:7], s[50:51], 0, v[6:7]
	global_load_dwordx4 v[12:15], v[6:7], off
	v_or_b32_e32 v6, s4, v43
	v_ashrrev_i32_e32 v7, 31, v6
	v_lshlrev_b64 v[6:7], 7, v[6:7]
	v_or_b32_e32 v6, v6, v40
	v_lshl_add_u64 v[0:1], v[0:1], 0, s[6:7]
	v_mov_b32_e32 v37, v7
	v_or_b32_e32 v36, s6, v6
	v_lshl_add_u64 v[0:1], v[0:1], 2, v[8:9]
	v_lshlrev_b64 v[36:37], 2, v[36:37]
	v_lshl_add_u64 v[38:39], s[14:15], 0, v[0:1]
	v_lshl_add_u64 v[0:1], s[16:17], 0, v[0:1]
	v_lshl_add_u64 v[56:57], s[48:49], 0, v[36:37]
	v_lshl_add_u64 v[58:59], s[50:51], 0, v[36:37]
	v_lshl_add_u64 v[6:7], v[6:7], 0, s[6:7]
	v_lshl_add_u64 v[6:7], v[6:7], 2, v[8:9]
	v_lshl_add_u64 v[62:63], s[14:15], 0, v[6:7]
	v_lshl_add_u64 v[6:7], s[16:17], 0, v[6:7]
	s_add_i32 s20, s5, 0x2000
	s_mul_i32 s2, s20, 0x2a00
	s_mul_hi_i32 s3, s20, 0x2a00
	s_add_u32 s2, s54, s2
	s_addc_u32 s3, s55, s3
	v_mov_b32_e32 v10, s6
	global_load_dwordx4 v[208:211], v[56:57], off
	s_nop 0
	global_load_dwordx4 v[212:215], v[58:59], off
	s_nop 0
	s_waitcnt vmcnt(3)
	global_store_dwordx4 v[38:39], v[2:5], off
	s_waitcnt vmcnt(3)
	global_store_dwordx4 v[0:1], v[12:15], off
	s_nop 0
	v_add_u32_e32 v0, s4, v44
	v_ashrrev_i32_e32 v1, 31, v0
	v_lshlrev_b64 v[0:1], 7, v[0:1]
	v_or_b32_e32 v0, v0, v40
	v_mov_b32_e32 v61, v1
	v_or_b32_e32 v60, s6, v0
	v_lshlrev_b64 v[60:61], 2, v[60:61]
	v_lshl_add_u64 v[64:65], s[48:49], 0, v[60:61]
	global_load_dwordx4 v[216:219], v[64:65], off
	s_nop 0
	v_lshl_add_u64 v[66:67], s[50:51], 0, v[60:61]
	global_load_dwordx4 v[220:223], v[66:67], off
	s_nop 0
	s_or_b32 s4, s4, 0x7f
	v_lshl_add_u64 v[0:1], v[0:1], 0, s[6:7]
	s_ashr_i32 s5, s4, 31
	v_lshl_add_u64 v[0:1], v[0:1], 2, v[8:9]
	s_lshl_b64 s[4:5], s[4:5], 7
	v_lshl_add_u64 v[68:69], s[16:17], 0, v[0:1]
	s_waitcnt vmcnt(5)
	global_store_dwordx4 v[62:63], v[208:211], off
	s_waitcnt vmcnt(5)
	global_store_dwordx4 v[6:7], v[212:215], off
	s_nop 0
	v_lshl_add_u64 v[6:7], s[14:15], 0, v[0:1]
	v_or3_b32 v1, s5, 0, 0
	v_or3_b32 v0, s4, v10, v152
	ds_write_b128 v29, v[2:5]
	ds_write_b128 v30, v[12:15] offset:35088
	ds_write_b128 v54, v[208:211] offset:17408
	ds_write_b128 v31, v[212:215] offset:35088
	s_waitcnt vmcnt(3)
	ds_write_b128 v32, v[216:219]
	s_waitcnt vmcnt(2)
	ds_write_b128 v33, v[220:223] offset:35088
	global_store_dwordx4 v[6:7], v[216:219], off
	global_store_dwordx4 v[68:69], v[220:223], off
	s_and_saveexec_b64 s[4:5], s[0:1]
	s_cbranch_execz .LBB0_340
	v_or_b32_e32 v2, s6, v253
	v_lshlrev_b32_e32 v2, 1, v2
	global_load_ushort v2, v2, s[2:3] offset:2048
	s_nop 0
	global_load_dword v4, v[20:21], off
	s_waitcnt vmcnt(1)
	v_lshlrev_b32_e32 v5, 16, v2
	v_mul_f32_e32 v2, v5, v5
	ds_bpermute_b32 v2, v16, v2
	s_waitcnt lgkmcnt(0)
	v_fmac_f32_e32 v2, v5, v5
	ds_bpermute_b32 v3, v17, v2
	s_waitcnt lgkmcnt(0)
	v_add_f32_e32 v2, v2, v3
	ds_bpermute_b32 v3, v18, v2
	s_waitcnt lgkmcnt(0)
	v_add_f32_e32 v2, v2, v3
	ds_bpermute_b32 v3, v19, v2
	s_waitcnt lgkmcnt(0)
	v_add_f32_e32 v2, v2, v3
	ds_bpermute_b32 v3, v26, v2
	s_waitcnt lgkmcnt(0)
	v_add_f32_e32 v2, v2, v3
	ds_bpermute_b32 v3, v27, v2
	s_waitcnt lgkmcnt(0)
	v_add_f32_e32 v2, v2, v3
	v_fmamk_f32 v2, v2, 0x3c800000, v34
	v_mul_f32_e32 v3, 0x4b800000, v2
	v_cmp_gt_f32_e32 vcc, s12, v2
	s_nop 1
	v_cndmask_b32_e32 v2, v2, v3, vcc
	v_rsq_f32_e32 v6, v2
	v_lshl_add_u64 v[2:3], v[0:1], 2, s[14:15]
	v_mul_f32_e32 v7, 0x45800000, v6
	v_cndmask_b32_e32 v6, v6, v7, vcc
	v_mul_f32_e32 v5, v6, v5
	s_waitcnt vmcnt(0)
	v_mul_f32_e32 v4, v4, v5
	ds_write_b32 v45, v4 offset:34816
	global_store_dword v[2:3], v4, off
